# scan inner loop rewrite + barrier release-before-invalidate + batched adaLN GEMV (k05)
# baseline (speedup 1.0000x reference)
.LBB0_72:
	s_mov_b64 s[98:99], 0x6000
	s_mov_b64 s[100:101], 0x1000
	v_mov_b64_e32 v[224:225], v[4:5]
	v_lshl_add_u64 v[226:227], v[224:225], 0, s[100:101]
	v_lshl_add_u64 v[228:229], v[226:227], 0, s[100:101]
	v_lshl_add_u64 v[230:231], v[228:229], 0, s[100:101]
	v_lshl_add_u64 v[232:233], v[230:231], 0, s[100:101]
	v_lshl_add_u64 v[234:235], v[232:233], 0, s[100:101]
	v_lshl_add_u64 v[236:237], v[234:235], 0, s[100:101]
	v_lshl_add_u64 v[238:239], v[236:237], 0, s[100:101]
	v_mov_b64_e32 v[240:241], v[6:7]
	v_mov_b32_e32 v208, 0
	v_mov_b32_e32 v209, 0
	v_mov_b32_e32 v210, 0
	v_mov_b32_e32 v211, 0
	v_mov_b32_e32 v212, 0
	v_mov_b32_e32 v213, 0
	v_mov_b32_e32 v214, 0
	v_mov_b32_e32 v215, 0
	v_mov_b32_e32 v216, 0
	v_mov_b32_e32 v217, 0
	v_mov_b32_e32 v218, 0
	v_mov_b32_e32 v219, 0
	v_mov_b32_e32 v220, 0
	v_mov_b32_e32 v221, 0
	v_mov_b32_e32 v222, 0
	v_mov_b32_e32 v223, 0
	global_load_dword v64, v[240:241], off
	v_lshl_add_u64 v[240:241], v[240:241], 0, s[98:99]
	global_load_dword v65, v[240:241], off
	v_lshl_add_u64 v[240:241], v[240:241], 0, s[98:99]
	global_load_dword v66, v[240:241], off
	v_lshl_add_u64 v[240:241], v[240:241], 0, s[98:99]
	global_load_dword v67, v[240:241], off
	v_lshl_add_u64 v[240:241], v[240:241], 0, s[98:99]
	global_load_dword v68, v[240:241], off
	v_lshl_add_u64 v[240:241], v[240:241], 0, s[98:99]
	global_load_dword v69, v[240:241], off
	v_lshl_add_u64 v[240:241], v[240:241], 0, s[98:99]
	global_load_dword v70, v[240:241], off
	v_lshl_add_u64 v[240:241], v[240:241], 0, s[98:99]
	global_load_dword v71, v[240:241], off
	v_lshl_add_u64 v[240:241], v[240:241], 0, s[98:99]
	global_load_dword v72, v[240:241], off
	v_lshl_add_u64 v[240:241], v[240:241], 0, s[98:99]
	global_load_dword v73, v[240:241], off
	v_lshl_add_u64 v[240:241], v[240:241], 0, s[98:99]
	global_load_dword v74, v[240:241], off
	v_lshl_add_u64 v[240:241], v[240:241], 0, s[98:99]
	global_load_dword v75, v[240:241], off
	v_lshl_add_u64 v[240:241], v[240:241], 0, s[98:99]
	global_load_dword v76, v[240:241], off
	v_lshl_add_u64 v[240:241], v[240:241], 0, s[98:99]
	global_load_dword v77, v[240:241], off
	v_lshl_add_u64 v[240:241], v[240:241], 0, s[98:99]
	global_load_dword v78, v[240:241], off
	v_lshl_add_u64 v[240:241], v[240:241], 0, s[98:99]
	global_load_dword v79, v[240:241], off
	v_lshl_add_u64 v[240:241], v[240:241], 0, s[98:99]
	global_load_dwordx4 v[80:83], v[224:225], off offset:0
	global_load_dwordx4 v[84:87], v[224:225], off offset:16
	global_load_dwordx4 v[88:91], v[224:225], off offset:32
	global_load_dwordx4 v[92:95], v[224:225], off offset:48
	global_load_dwordx4 v[96:99], v[226:227], off offset:0
	global_load_dwordx4 v[100:103], v[226:227], off offset:16
	global_load_dwordx4 v[104:107], v[226:227], off offset:32
	global_load_dwordx4 v[108:111], v[226:227], off offset:48
	global_load_dwordx4 v[112:115], v[228:229], off offset:0
	global_load_dwordx4 v[116:119], v[228:229], off offset:16
	global_load_dwordx4 v[120:123], v[228:229], off offset:32
	global_load_dwordx4 v[124:127], v[228:229], off offset:48
	global_load_dwordx4 v[128:131], v[230:231], off offset:0
	global_load_dwordx4 v[132:135], v[230:231], off offset:16
	global_load_dwordx4 v[136:139], v[230:231], off offset:32
	global_load_dwordx4 v[140:143], v[230:231], off offset:48
	global_load_dwordx4 v[144:147], v[232:233], off offset:0
	global_load_dwordx4 v[148:151], v[232:233], off offset:16
	global_load_dwordx4 v[152:155], v[232:233], off offset:32
	global_load_dwordx4 v[156:159], v[232:233], off offset:48
	global_load_dwordx4 v[160:163], v[234:235], off offset:0
	global_load_dwordx4 v[164:167], v[234:235], off offset:16
	global_load_dwordx4 v[168:171], v[234:235], off offset:32
	global_load_dwordx4 v[172:175], v[234:235], off offset:48
	global_load_dwordx4 v[176:179], v[236:237], off offset:0
	global_load_dwordx4 v[180:183], v[236:237], off offset:16
	global_load_dwordx4 v[184:187], v[236:237], off offset:32
	global_load_dwordx4 v[188:191], v[236:237], off offset:48
	global_load_dwordx4 v[192:195], v[238:239], off offset:0
	global_load_dwordx4 v[196:199], v[238:239], off offset:16
	global_load_dwordx4 v[200:203], v[238:239], off offset:32
	global_load_dwordx4 v[204:207], v[238:239], off offset:48
	s_waitcnt vmcnt(0)
	v_pk_fma_f32 v[208:209], v[80:81], v[64:65], v[208:209]
	v_pk_fma_f32 v[210:211], v[96:97], v[64:65], v[210:211]
	v_pk_fma_f32 v[212:213], v[112:113], v[64:65], v[212:213]
	v_pk_fma_f32 v[214:215], v[128:129], v[64:65], v[214:215]
	v_pk_fma_f32 v[216:217], v[144:145], v[64:65], v[216:217]
	v_pk_fma_f32 v[218:219], v[160:161], v[64:65], v[218:219]
	v_pk_fma_f32 v[220:221], v[176:177], v[64:65], v[220:221]
	v_pk_fma_f32 v[222:223], v[192:193], v[64:65], v[222:223]
	v_pk_fma_f32 v[208:209], v[82:83], v[66:67], v[208:209]
	v_pk_fma_f32 v[210:211], v[98:99], v[66:67], v[210:211]
	v_pk_fma_f32 v[212:213], v[114:115], v[66:67], v[212:213]
	v_pk_fma_f32 v[214:215], v[130:131], v[66:67], v[214:215]
	v_pk_fma_f32 v[216:217], v[146:147], v[66:67], v[216:217]
	v_pk_fma_f32 v[218:219], v[162:163], v[66:67], v[218:219]
	v_pk_fma_f32 v[220:221], v[178:179], v[66:67], v[220:221]
	v_pk_fma_f32 v[222:223], v[194:195], v[66:67], v[222:223]
	v_pk_fma_f32 v[208:209], v[84:85], v[68:69], v[208:209]
	v_pk_fma_f32 v[210:211], v[100:101], v[68:69], v[210:211]
	v_pk_fma_f32 v[212:213], v[116:117], v[68:69], v[212:213]
	v_pk_fma_f32 v[214:215], v[132:133], v[68:69], v[214:215]
	v_pk_fma_f32 v[216:217], v[148:149], v[68:69], v[216:217]
	v_pk_fma_f32 v[218:219], v[164:165], v[68:69], v[218:219]
	v_pk_fma_f32 v[220:221], v[180:181], v[68:69], v[220:221]
	v_pk_fma_f32 v[222:223], v[196:197], v[68:69], v[222:223]
	v_pk_fma_f32 v[208:209], v[86:87], v[70:71], v[208:209]
	v_pk_fma_f32 v[210:211], v[102:103], v[70:71], v[210:211]
	v_pk_fma_f32 v[212:213], v[118:119], v[70:71], v[212:213]
	v_pk_fma_f32 v[214:215], v[134:135], v[70:71], v[214:215]
	v_pk_fma_f32 v[216:217], v[150:151], v[70:71], v[216:217]
	v_pk_fma_f32 v[218:219], v[166:167], v[70:71], v[218:219]
	v_pk_fma_f32 v[220:221], v[182:183], v[70:71], v[220:221]
	v_pk_fma_f32 v[222:223], v[198:199], v[70:71], v[222:223]
	v_pk_fma_f32 v[208:209], v[88:89], v[72:73], v[208:209]
	v_pk_fma_f32 v[210:211], v[104:105], v[72:73], v[210:211]
	v_pk_fma_f32 v[212:213], v[120:121], v[72:73], v[212:213]
	v_pk_fma_f32 v[214:215], v[136:137], v[72:73], v[214:215]
	v_pk_fma_f32 v[216:217], v[152:153], v[72:73], v[216:217]
	v_pk_fma_f32 v[218:219], v[168:169], v[72:73], v[218:219]
	v_pk_fma_f32 v[220:221], v[184:185], v[72:73], v[220:221]
	v_pk_fma_f32 v[222:223], v[200:201], v[72:73], v[222:223]
	v_pk_fma_f32 v[208:209], v[90:91], v[74:75], v[208:209]
	v_pk_fma_f32 v[210:211], v[106:107], v[74:75], v[210:211]
	v_pk_fma_f32 v[212:213], v[122:123], v[74:75], v[212:213]
	v_pk_fma_f32 v[214:215], v[138:139], v[74:75], v[214:215]
	v_pk_fma_f32 v[216:217], v[154:155], v[74:75], v[216:217]
	v_pk_fma_f32 v[218:219], v[170:171], v[74:75], v[218:219]
	v_pk_fma_f32 v[220:221], v[186:187], v[74:75], v[220:221]
	v_pk_fma_f32 v[222:223], v[202:203], v[74:75], v[222:223]
	v_pk_fma_f32 v[208:209], v[92:93], v[76:77], v[208:209]
	v_pk_fma_f32 v[210:211], v[108:109], v[76:77], v[210:211]
	v_pk_fma_f32 v[212:213], v[124:125], v[76:77], v[212:213]
	v_pk_fma_f32 v[214:215], v[140:141], v[76:77], v[214:215]
	v_pk_fma_f32 v[216:217], v[156:157], v[76:77], v[216:217]
	v_pk_fma_f32 v[218:219], v[172:173], v[76:77], v[218:219]
	v_pk_fma_f32 v[220:221], v[188:189], v[76:77], v[220:221]
	v_pk_fma_f32 v[222:223], v[204:205], v[76:77], v[222:223]
	v_pk_fma_f32 v[208:209], v[94:95], v[78:79], v[208:209]
	v_pk_fma_f32 v[210:211], v[110:111], v[78:79], v[210:211]
	v_pk_fma_f32 v[212:213], v[126:127], v[78:79], v[212:213]
	v_pk_fma_f32 v[214:215], v[142:143], v[78:79], v[214:215]
	v_pk_fma_f32 v[216:217], v[158:159], v[78:79], v[216:217]
	v_pk_fma_f32 v[218:219], v[174:175], v[78:79], v[218:219]
	v_pk_fma_f32 v[220:221], v[190:191], v[78:79], v[220:221]
	v_pk_fma_f32 v[222:223], v[206:207], v[78:79], v[222:223]
	global_load_dword v64, v[240:241], off
	v_lshl_add_u64 v[240:241], v[240:241], 0, s[98:99]
	global_load_dword v65, v[240:241], off
	v_lshl_add_u64 v[240:241], v[240:241], 0, s[98:99]
	global_load_dword v66, v[240:241], off
	v_lshl_add_u64 v[240:241], v[240:241], 0, s[98:99]
	global_load_dword v67, v[240:241], off
	v_lshl_add_u64 v[240:241], v[240:241], 0, s[98:99]
	global_load_dword v68, v[240:241], off
	v_lshl_add_u64 v[240:241], v[240:241], 0, s[98:99]
	global_load_dword v69, v[240:241], off
	v_lshl_add_u64 v[240:241], v[240:241], 0, s[98:99]
	global_load_dword v70, v[240:241], off
	v_lshl_add_u64 v[240:241], v[240:241], 0, s[98:99]
	global_load_dword v71, v[240:241], off
	v_lshl_add_u64 v[240:241], v[240:241], 0, s[98:99]
	global_load_dword v72, v[240:241], off
	v_lshl_add_u64 v[240:241], v[240:241], 0, s[98:99]
	global_load_dword v73, v[240:241], off
	v_lshl_add_u64 v[240:241], v[240:241], 0, s[98:99]
	global_load_dword v74, v[240:241], off
	v_lshl_add_u64 v[240:241], v[240:241], 0, s[98:99]
	global_load_dword v75, v[240:241], off
	v_lshl_add_u64 v[240:241], v[240:241], 0, s[98:99]
	global_load_dword v76, v[240:241], off
	v_lshl_add_u64 v[240:241], v[240:241], 0, s[98:99]
	global_load_dword v77, v[240:241], off
	v_lshl_add_u64 v[240:241], v[240:241], 0, s[98:99]
	global_load_dword v78, v[240:241], off
	v_lshl_add_u64 v[240:241], v[240:241], 0, s[98:99]
	global_load_dword v79, v[240:241], off
	v_lshl_add_u64 v[240:241], v[240:241], 0, s[98:99]
	global_load_dwordx4 v[80:83], v[224:225], off offset:64
	global_load_dwordx4 v[84:87], v[224:225], off offset:80
	global_load_dwordx4 v[88:91], v[224:225], off offset:96
	global_load_dwordx4 v[92:95], v[224:225], off offset:112
	global_load_dwordx4 v[96:99], v[226:227], off offset:64
	global_load_dwordx4 v[100:103], v[226:227], off offset:80
	global_load_dwordx4 v[104:107], v[226:227], off offset:96
	global_load_dwordx4 v[108:111], v[226:227], off offset:112
	global_load_dwordx4 v[112:115], v[228:229], off offset:64
	global_load_dwordx4 v[116:119], v[228:229], off offset:80
	global_load_dwordx4 v[120:123], v[228:229], off offset:96
	global_load_dwordx4 v[124:127], v[228:229], off offset:112
	global_load_dwordx4 v[128:131], v[230:231], off offset:64
	global_load_dwordx4 v[132:135], v[230:231], off offset:80
	global_load_dwordx4 v[136:139], v[230:231], off offset:96
	global_load_dwordx4 v[140:143], v[230:231], off offset:112
	global_load_dwordx4 v[144:147], v[232:233], off offset:64
	global_load_dwordx4 v[148:151], v[232:233], off offset:80
	global_load_dwordx4 v[152:155], v[232:233], off offset:96
	global_load_dwordx4 v[156:159], v[232:233], off offset:112
	global_load_dwordx4 v[160:163], v[234:235], off offset:64
	global_load_dwordx4 v[164:167], v[234:235], off offset:80
	global_load_dwordx4 v[168:171], v[234:235], off offset:96
	global_load_dwordx4 v[172:175], v[234:235], off offset:112
	global_load_dwordx4 v[176:179], v[236:237], off offset:64
	global_load_dwordx4 v[180:183], v[236:237], off offset:80
	global_load_dwordx4 v[184:187], v[236:237], off offset:96
	global_load_dwordx4 v[188:191], v[236:237], off offset:112
	global_load_dwordx4 v[192:195], v[238:239], off offset:64
	global_load_dwordx4 v[196:199], v[238:239], off offset:80
	global_load_dwordx4 v[200:203], v[238:239], off offset:96
	global_load_dwordx4 v[204:207], v[238:239], off offset:112
	s_waitcnt vmcnt(0)
	v_pk_fma_f32 v[208:209], v[80:81], v[64:65], v[208:209]
	v_pk_fma_f32 v[210:211], v[96:97], v[64:65], v[210:211]
	v_pk_fma_f32 v[212:213], v[112:113], v[64:65], v[212:213]
	v_pk_fma_f32 v[214:215], v[128:129], v[64:65], v[214:215]
	v_pk_fma_f32 v[216:217], v[144:145], v[64:65], v[216:217]
	v_pk_fma_f32 v[218:219], v[160:161], v[64:65], v[218:219]
	v_pk_fma_f32 v[220:221], v[176:177], v[64:65], v[220:221]
	v_pk_fma_f32 v[222:223], v[192:193], v[64:65], v[222:223]
	v_pk_fma_f32 v[208:209], v[82:83], v[66:67], v[208:209]
	v_pk_fma_f32 v[210:211], v[98:99], v[66:67], v[210:211]
	v_pk_fma_f32 v[212:213], v[114:115], v[66:67], v[212:213]
	v_pk_fma_f32 v[214:215], v[130:131], v[66:67], v[214:215]
	v_pk_fma_f32 v[216:217], v[146:147], v[66:67], v[216:217]
	v_pk_fma_f32 v[218:219], v[162:163], v[66:67], v[218:219]
	v_pk_fma_f32 v[220:221], v[178:179], v[66:67], v[220:221]
	v_pk_fma_f32 v[222:223], v[194:195], v[66:67], v[222:223]
	v_pk_fma_f32 v[208:209], v[84:85], v[68:69], v[208:209]
	v_pk_fma_f32 v[210:211], v[100:101], v[68:69], v[210:211]
	v_pk_fma_f32 v[212:213], v[116:117], v[68:69], v[212:213]
	v_pk_fma_f32 v[214:215], v[132:133], v[68:69], v[214:215]
	v_pk_fma_f32 v[216:217], v[148:149], v[68:69], v[216:217]
	v_pk_fma_f32 v[218:219], v[164:165], v[68:69], v[218:219]
	v_pk_fma_f32 v[220:221], v[180:181], v[68:69], v[220:221]
	v_pk_fma_f32 v[222:223], v[196:197], v[68:69], v[222:223]
	v_pk_fma_f32 v[208:209], v[86:87], v[70:71], v[208:209]
	v_pk_fma_f32 v[210:211], v[102:103], v[70:71], v[210:211]
	v_pk_fma_f32 v[212:213], v[118:119], v[70:71], v[212:213]
	v_pk_fma_f32 v[214:215], v[134:135], v[70:71], v[214:215]
	v_pk_fma_f32 v[216:217], v[150:151], v[70:71], v[216:217]
	v_pk_fma_f32 v[218:219], v[166:167], v[70:71], v[218:219]
	v_pk_fma_f32 v[220:221], v[182:183], v[70:71], v[220:221]
	v_pk_fma_f32 v[222:223], v[198:199], v[70:71], v[222:223]
	v_pk_fma_f32 v[208:209], v[88:89], v[72:73], v[208:209]
	v_pk_fma_f32 v[210:211], v[104:105], v[72:73], v[210:211]
	v_pk_fma_f32 v[212:213], v[120:121], v[72:73], v[212:213]
	v_pk_fma_f32 v[214:215], v[136:137], v[72:73], v[214:215]
	v_pk_fma_f32 v[216:217], v[152:153], v[72:73], v[216:217]
	v_pk_fma_f32 v[218:219], v[168:169], v[72:73], v[218:219]
	v_pk_fma_f32 v[220:221], v[184:185], v[72:73], v[220:221]
	v_pk_fma_f32 v[222:223], v[200:201], v[72:73], v[222:223]
	v_pk_fma_f32 v[208:209], v[90:91], v[74:75], v[208:209]
	v_pk_fma_f32 v[210:211], v[106:107], v[74:75], v[210:211]
	v_pk_fma_f32 v[212:213], v[122:123], v[74:75], v[212:213]
	v_pk_fma_f32 v[214:215], v[138:139], v[74:75], v[214:215]
	v_pk_fma_f32 v[216:217], v[154:155], v[74:75], v[216:217]
	v_pk_fma_f32 v[218:219], v[170:171], v[74:75], v[218:219]
	v_pk_fma_f32 v[220:221], v[186:187], v[74:75], v[220:221]
	v_pk_fma_f32 v[222:223], v[202:203], v[74:75], v[222:223]
	v_pk_fma_f32 v[208:209], v[92:93], v[76:77], v[208:209]
	v_pk_fma_f32 v[210:211], v[108:109], v[76:77], v[210:211]
	v_pk_fma_f32 v[212:213], v[124:125], v[76:77], v[212:213]
	v_pk_fma_f32 v[214:215], v[140:141], v[76:77], v[214:215]
	v_pk_fma_f32 v[216:217], v[156:157], v[76:77], v[216:217]
	v_pk_fma_f32 v[218:219], v[172:173], v[76:77], v[218:219]
	v_pk_fma_f32 v[220:221], v[188:189], v[76:77], v[220:221]
	v_pk_fma_f32 v[222:223], v[204:205], v[76:77], v[222:223]
	v_pk_fma_f32 v[208:209], v[94:95], v[78:79], v[208:209]
	v_pk_fma_f32 v[210:211], v[110:111], v[78:79], v[210:211]
	v_pk_fma_f32 v[212:213], v[126:127], v[78:79], v[212:213]
	v_pk_fma_f32 v[214:215], v[142:143], v[78:79], v[214:215]
	v_pk_fma_f32 v[216:217], v[158:159], v[78:79], v[216:217]
	v_pk_fma_f32 v[218:219], v[174:175], v[78:79], v[218:219]
	v_pk_fma_f32 v[220:221], v[190:191], v[78:79], v[220:221]
	v_pk_fma_f32 v[222:223], v[206:207], v[78:79], v[222:223]
	global_load_dword v64, v[240:241], off
	v_lshl_add_u64 v[240:241], v[240:241], 0, s[98:99]
	global_load_dword v65, v[240:241], off
	v_lshl_add_u64 v[240:241], v[240:241], 0, s[98:99]
	global_load_dword v66, v[240:241], off
	v_lshl_add_u64 v[240:241], v[240:241], 0, s[98:99]
	global_load_dword v67, v[240:241], off
	v_lshl_add_u64 v[240:241], v[240:241], 0, s[98:99]
	global_load_dword v68, v[240:241], off
	v_lshl_add_u64 v[240:241], v[240:241], 0, s[98:99]
	global_load_dword v69, v[240:241], off
	v_lshl_add_u64 v[240:241], v[240:241], 0, s[98:99]
	global_load_dword v70, v[240:241], off
	v_lshl_add_u64 v[240:241], v[240:241], 0, s[98:99]
	global_load_dword v71, v[240:241], off
	v_lshl_add_u64 v[240:241], v[240:241], 0, s[98:99]
	global_load_dword v72, v[240:241], off
	v_lshl_add_u64 v[240:241], v[240:241], 0, s[98:99]
	global_load_dword v73, v[240:241], off
	v_lshl_add_u64 v[240:241], v[240:241], 0, s[98:99]
	global_load_dword v74, v[240:241], off
	v_lshl_add_u64 v[240:241], v[240:241], 0, s[98:99]
	global_load_dword v75, v[240:241], off
	v_lshl_add_u64 v[240:241], v[240:241], 0, s[98:99]
	global_load_dword v76, v[240:241], off
	v_lshl_add_u64 v[240:241], v[240:241], 0, s[98:99]
	global_load_dword v77, v[240:241], off
	v_lshl_add_u64 v[240:241], v[240:241], 0, s[98:99]
	global_load_dword v78, v[240:241], off
	v_lshl_add_u64 v[240:241], v[240:241], 0, s[98:99]
	global_load_dword v79, v[240:241], off
	v_lshl_add_u64 v[240:241], v[240:241], 0, s[98:99]
	global_load_dwordx4 v[80:83], v[224:225], off offset:128
	global_load_dwordx4 v[84:87], v[224:225], off offset:144
	global_load_dwordx4 v[88:91], v[224:225], off offset:160
	global_load_dwordx4 v[92:95], v[224:225], off offset:176
	global_load_dwordx4 v[96:99], v[226:227], off offset:128
	global_load_dwordx4 v[100:103], v[226:227], off offset:144
	global_load_dwordx4 v[104:107], v[226:227], off offset:160
	global_load_dwordx4 v[108:111], v[226:227], off offset:176
	global_load_dwordx4 v[112:115], v[228:229], off offset:128
	global_load_dwordx4 v[116:119], v[228:229], off offset:144
	global_load_dwordx4 v[120:123], v[228:229], off offset:160
	global_load_dwordx4 v[124:127], v[228:229], off offset:176
	global_load_dwordx4 v[128:131], v[230:231], off offset:128
	global_load_dwordx4 v[132:135], v[230:231], off offset:144
	global_load_dwordx4 v[136:139], v[230:231], off offset:160
	global_load_dwordx4 v[140:143], v[230:231], off offset:176
	global_load_dwordx4 v[144:147], v[232:233], off offset:128
	global_load_dwordx4 v[148:151], v[232:233], off offset:144
	global_load_dwordx4 v[152:155], v[232:233], off offset:160
	global_load_dwordx4 v[156:159], v[232:233], off offset:176
	global_load_dwordx4 v[160:163], v[234:235], off offset:128
	global_load_dwordx4 v[164:167], v[234:235], off offset:144
	global_load_dwordx4 v[168:171], v[234:235], off offset:160
	global_load_dwordx4 v[172:175], v[234:235], off offset:176
	global_load_dwordx4 v[176:179], v[236:237], off offset:128
	global_load_dwordx4 v[180:183], v[236:237], off offset:144
	global_load_dwordx4 v[184:187], v[236:237], off offset:160
	global_load_dwordx4 v[188:191], v[236:237], off offset:176
	global_load_dwordx4 v[192:195], v[238:239], off offset:128
	global_load_dwordx4 v[196:199], v[238:239], off offset:144
	global_load_dwordx4 v[200:203], v[238:239], off offset:160
	global_load_dwordx4 v[204:207], v[238:239], off offset:176
	s_waitcnt vmcnt(0)
	v_pk_fma_f32 v[208:209], v[80:81], v[64:65], v[208:209]
	v_pk_fma_f32 v[210:211], v[96:97], v[64:65], v[210:211]
	v_pk_fma_f32 v[212:213], v[112:113], v[64:65], v[212:213]
	v_pk_fma_f32 v[214:215], v[128:129], v[64:65], v[214:215]
	v_pk_fma_f32 v[216:217], v[144:145], v[64:65], v[216:217]
	v_pk_fma_f32 v[218:219], v[160:161], v[64:65], v[218:219]
	v_pk_fma_f32 v[220:221], v[176:177], v[64:65], v[220:221]
	v_pk_fma_f32 v[222:223], v[192:193], v[64:65], v[222:223]
	v_pk_fma_f32 v[208:209], v[82:83], v[66:67], v[208:209]
	v_pk_fma_f32 v[210:211], v[98:99], v[66:67], v[210:211]
	v_pk_fma_f32 v[212:213], v[114:115], v[66:67], v[212:213]
	v_pk_fma_f32 v[214:215], v[130:131], v[66:67], v[214:215]
	v_pk_fma_f32 v[216:217], v[146:147], v[66:67], v[216:217]
	v_pk_fma_f32 v[218:219], v[162:163], v[66:67], v[218:219]
	v_pk_fma_f32 v[220:221], v[178:179], v[66:67], v[220:221]
	v_pk_fma_f32 v[222:223], v[194:195], v[66:67], v[222:223]
	v_pk_fma_f32 v[208:209], v[84:85], v[68:69], v[208:209]
	v_pk_fma_f32 v[210:211], v[100:101], v[68:69], v[210:211]
	v_pk_fma_f32 v[212:213], v[116:117], v[68:69], v[212:213]
	v_pk_fma_f32 v[214:215], v[132:133], v[68:69], v[214:215]
	v_pk_fma_f32 v[216:217], v[148:149], v[68:69], v[216:217]
	v_pk_fma_f32 v[218:219], v[164:165], v[68:69], v[218:219]
	v_pk_fma_f32 v[220:221], v[180:181], v[68:69], v[220:221]
	v_pk_fma_f32 v[222:223], v[196:197], v[68:69], v[222:223]
	v_pk_fma_f32 v[208:209], v[86:87], v[70:71], v[208:209]
	v_pk_fma_f32 v[210:211], v[102:103], v[70:71], v[210:211]
	v_pk_fma_f32 v[212:213], v[118:119], v[70:71], v[212:213]
	v_pk_fma_f32 v[214:215], v[134:135], v[70:71], v[214:215]
	v_pk_fma_f32 v[216:217], v[150:151], v[70:71], v[216:217]
	v_pk_fma_f32 v[218:219], v[166:167], v[70:71], v[218:219]
	v_pk_fma_f32 v[220:221], v[182:183], v[70:71], v[220:221]
	v_pk_fma_f32 v[222:223], v[198:199], v[70:71], v[222:223]
	v_pk_fma_f32 v[208:209], v[88:89], v[72:73], v[208:209]
	v_pk_fma_f32 v[210:211], v[104:105], v[72:73], v[210:211]
	v_pk_fma_f32 v[212:213], v[120:121], v[72:73], v[212:213]
	v_pk_fma_f32 v[214:215], v[136:137], v[72:73], v[214:215]
	v_pk_fma_f32 v[216:217], v[152:153], v[72:73], v[216:217]
	v_pk_fma_f32 v[218:219], v[168:169], v[72:73], v[218:219]
	v_pk_fma_f32 v[220:221], v[184:185], v[72:73], v[220:221]
	v_pk_fma_f32 v[222:223], v[200:201], v[72:73], v[222:223]
	v_pk_fma_f32 v[208:209], v[90:91], v[74:75], v[208:209]
	v_pk_fma_f32 v[210:211], v[106:107], v[74:75], v[210:211]
	v_pk_fma_f32 v[212:213], v[122:123], v[74:75], v[212:213]
	v_pk_fma_f32 v[214:215], v[138:139], v[74:75], v[214:215]
	v_pk_fma_f32 v[216:217], v[154:155], v[74:75], v[216:217]
	v_pk_fma_f32 v[218:219], v[170:171], v[74:75], v[218:219]
	v_pk_fma_f32 v[220:221], v[186:187], v[74:75], v[220:221]
	v_pk_fma_f32 v[222:223], v[202:203], v[74:75], v[222:223]
	v_pk_fma_f32 v[208:209], v[92:93], v[76:77], v[208:209]
	v_pk_fma_f32 v[210:211], v[108:109], v[76:77], v[210:211]
	v_pk_fma_f32 v[212:213], v[124:125], v[76:77], v[212:213]
	v_pk_fma_f32 v[214:215], v[140:141], v[76:77], v[214:215]
	v_pk_fma_f32 v[216:217], v[156:157], v[76:77], v[216:217]
	v_pk_fma_f32 v[218:219], v[172:173], v[76:77], v[218:219]
	v_pk_fma_f32 v[220:221], v[188:189], v[76:77], v[220:221]
	v_pk_fma_f32 v[222:223], v[204:205], v[76:77], v[222:223]
	v_pk_fma_f32 v[208:209], v[94:95], v[78:79], v[208:209]
	v_pk_fma_f32 v[210:211], v[110:111], v[78:79], v[210:211]
	v_pk_fma_f32 v[212:213], v[126:127], v[78:79], v[212:213]
	v_pk_fma_f32 v[214:215], v[142:143], v[78:79], v[214:215]
	v_pk_fma_f32 v[216:217], v[158:159], v[78:79], v[216:217]
	v_pk_fma_f32 v[218:219], v[174:175], v[78:79], v[218:219]
	v_pk_fma_f32 v[220:221], v[190:191], v[78:79], v[220:221]
	v_pk_fma_f32 v[222:223], v[206:207], v[78:79], v[222:223]
	global_load_dword v64, v[240:241], off
	v_lshl_add_u64 v[240:241], v[240:241], 0, s[98:99]
	global_load_dword v65, v[240:241], off
	v_lshl_add_u64 v[240:241], v[240:241], 0, s[98:99]
	global_load_dword v66, v[240:241], off
	v_lshl_add_u64 v[240:241], v[240:241], 0, s[98:99]
	global_load_dword v67, v[240:241], off
	v_lshl_add_u64 v[240:241], v[240:241], 0, s[98:99]
	global_load_dword v68, v[240:241], off
	v_lshl_add_u64 v[240:241], v[240:241], 0, s[98:99]
	global_load_dword v69, v[240:241], off
	v_lshl_add_u64 v[240:241], v[240:241], 0, s[98:99]
	global_load_dword v70, v[240:241], off
	v_lshl_add_u64 v[240:241], v[240:241], 0, s[98:99]
	global_load_dword v71, v[240:241], off
	v_lshl_add_u64 v[240:241], v[240:241], 0, s[98:99]
	global_load_dword v72, v[240:241], off
	v_lshl_add_u64 v[240:241], v[240:241], 0, s[98:99]
	global_load_dword v73, v[240:241], off
	v_lshl_add_u64 v[240:241], v[240:241], 0, s[98:99]
	global_load_dword v74, v[240:241], off
	v_lshl_add_u64 v[240:241], v[240:241], 0, s[98:99]
	global_load_dword v75, v[240:241], off
	v_lshl_add_u64 v[240:241], v[240:241], 0, s[98:99]
	global_load_dword v76, v[240:241], off
	v_lshl_add_u64 v[240:241], v[240:241], 0, s[98:99]
	global_load_dword v77, v[240:241], off
	v_lshl_add_u64 v[240:241], v[240:241], 0, s[98:99]
	global_load_dword v78, v[240:241], off
	v_lshl_add_u64 v[240:241], v[240:241], 0, s[98:99]
	global_load_dword v79, v[240:241], off
	v_lshl_add_u64 v[240:241], v[240:241], 0, s[98:99]
	global_load_dwordx4 v[80:83], v[224:225], off offset:192
	global_load_dwordx4 v[84:87], v[224:225], off offset:208
	global_load_dwordx4 v[88:91], v[224:225], off offset:224
	global_load_dwordx4 v[92:95], v[224:225], off offset:240
	global_load_dwordx4 v[96:99], v[226:227], off offset:192
	global_load_dwordx4 v[100:103], v[226:227], off offset:208
	global_load_dwordx4 v[104:107], v[226:227], off offset:224
	global_load_dwordx4 v[108:111], v[226:227], off offset:240
	global_load_dwordx4 v[112:115], v[228:229], off offset:192
	global_load_dwordx4 v[116:119], v[228:229], off offset:208
	global_load_dwordx4 v[120:123], v[228:229], off offset:224
	global_load_dwordx4 v[124:127], v[228:229], off offset:240
	global_load_dwordx4 v[128:131], v[230:231], off offset:192
	global_load_dwordx4 v[132:135], v[230:231], off offset:208
	global_load_dwordx4 v[136:139], v[230:231], off offset:224
	global_load_dwordx4 v[140:143], v[230:231], off offset:240
	global_load_dwordx4 v[144:147], v[232:233], off offset:192
	global_load_dwordx4 v[148:151], v[232:233], off offset:208
	global_load_dwordx4 v[152:155], v[232:233], off offset:224
	global_load_dwordx4 v[156:159], v[232:233], off offset:240
	global_load_dwordx4 v[160:163], v[234:235], off offset:192
	global_load_dwordx4 v[164:167], v[234:235], off offset:208
	global_load_dwordx4 v[168:171], v[234:235], off offset:224
	global_load_dwordx4 v[172:175], v[234:235], off offset:240
	global_load_dwordx4 v[176:179], v[236:237], off offset:192
	global_load_dwordx4 v[180:183], v[236:237], off offset:208
	global_load_dwordx4 v[184:187], v[236:237], off offset:224
	global_load_dwordx4 v[188:191], v[236:237], off offset:240
	global_load_dwordx4 v[192:195], v[238:239], off offset:192
	global_load_dwordx4 v[196:199], v[238:239], off offset:208
	global_load_dwordx4 v[200:203], v[238:239], off offset:224
	global_load_dwordx4 v[204:207], v[238:239], off offset:240
	s_waitcnt vmcnt(0)
	v_pk_fma_f32 v[208:209], v[80:81], v[64:65], v[208:209]
	v_pk_fma_f32 v[210:211], v[96:97], v[64:65], v[210:211]
	v_pk_fma_f32 v[212:213], v[112:113], v[64:65], v[212:213]
	v_pk_fma_f32 v[214:215], v[128:129], v[64:65], v[214:215]
	v_pk_fma_f32 v[216:217], v[144:145], v[64:65], v[216:217]
	v_pk_fma_f32 v[218:219], v[160:161], v[64:65], v[218:219]
	v_pk_fma_f32 v[220:221], v[176:177], v[64:65], v[220:221]
	v_pk_fma_f32 v[222:223], v[192:193], v[64:65], v[222:223]
	v_pk_fma_f32 v[208:209], v[82:83], v[66:67], v[208:209]
	v_pk_fma_f32 v[210:211], v[98:99], v[66:67], v[210:211]
	v_pk_fma_f32 v[212:213], v[114:115], v[66:67], v[212:213]
	v_pk_fma_f32 v[214:215], v[130:131], v[66:67], v[214:215]
	v_pk_fma_f32 v[216:217], v[146:147], v[66:67], v[216:217]
	v_pk_fma_f32 v[218:219], v[162:163], v[66:67], v[218:219]
	v_pk_fma_f32 v[220:221], v[178:179], v[66:67], v[220:221]
	v_pk_fma_f32 v[222:223], v[194:195], v[66:67], v[222:223]
	v_pk_fma_f32 v[208:209], v[84:85], v[68:69], v[208:209]
	v_pk_fma_f32 v[210:211], v[100:101], v[68:69], v[210:211]
	v_pk_fma_f32 v[212:213], v[116:117], v[68:69], v[212:213]
	v_pk_fma_f32 v[214:215], v[132:133], v[68:69], v[214:215]
	v_pk_fma_f32 v[216:217], v[148:149], v[68:69], v[216:217]
	v_pk_fma_f32 v[218:219], v[164:165], v[68:69], v[218:219]
	v_pk_fma_f32 v[220:221], v[180:181], v[68:69], v[220:221]
	v_pk_fma_f32 v[222:223], v[196:197], v[68:69], v[222:223]
	v_pk_fma_f32 v[208:209], v[86:87], v[70:71], v[208:209]
	v_pk_fma_f32 v[210:211], v[102:103], v[70:71], v[210:211]
	v_pk_fma_f32 v[212:213], v[118:119], v[70:71], v[212:213]
	v_pk_fma_f32 v[214:215], v[134:135], v[70:71], v[214:215]
	v_pk_fma_f32 v[216:217], v[150:151], v[70:71], v[216:217]
	v_pk_fma_f32 v[218:219], v[166:167], v[70:71], v[218:219]
	v_pk_fma_f32 v[220:221], v[182:183], v[70:71], v[220:221]
	v_pk_fma_f32 v[222:223], v[198:199], v[70:71], v[222:223]
	v_pk_fma_f32 v[208:209], v[88:89], v[72:73], v[208:209]
	v_pk_fma_f32 v[210:211], v[104:105], v[72:73], v[210:211]
	v_pk_fma_f32 v[212:213], v[120:121], v[72:73], v[212:213]
	v_pk_fma_f32 v[214:215], v[136:137], v[72:73], v[214:215]
	v_pk_fma_f32 v[216:217], v[152:153], v[72:73], v[216:217]
	v_pk_fma_f32 v[218:219], v[168:169], v[72:73], v[218:219]
	v_pk_fma_f32 v[220:221], v[184:185], v[72:73], v[220:221]
	v_pk_fma_f32 v[222:223], v[200:201], v[72:73], v[222:223]
	v_pk_fma_f32 v[208:209], v[90:91], v[74:75], v[208:209]
	v_pk_fma_f32 v[210:211], v[106:107], v[74:75], v[210:211]
	v_pk_fma_f32 v[212:213], v[122:123], v[74:75], v[212:213]
	v_pk_fma_f32 v[214:215], v[138:139], v[74:75], v[214:215]
	v_pk_fma_f32 v[216:217], v[154:155], v[74:75], v[216:217]
	v_pk_fma_f32 v[218:219], v[170:171], v[74:75], v[218:219]
	v_pk_fma_f32 v[220:221], v[186:187], v[74:75], v[220:221]
	v_pk_fma_f32 v[222:223], v[202:203], v[74:75], v[222:223]
	v_pk_fma_f32 v[208:209], v[92:93], v[76:77], v[208:209]
	v_pk_fma_f32 v[210:211], v[108:109], v[76:77], v[210:211]
	v_pk_fma_f32 v[212:213], v[124:125], v[76:77], v[212:213]
	v_pk_fma_f32 v[214:215], v[140:141], v[76:77], v[214:215]
	v_pk_fma_f32 v[216:217], v[156:157], v[76:77], v[216:217]
	v_pk_fma_f32 v[218:219], v[172:173], v[76:77], v[218:219]
	v_pk_fma_f32 v[220:221], v[188:189], v[76:77], v[220:221]
	v_pk_fma_f32 v[222:223], v[204:205], v[76:77], v[222:223]
	v_pk_fma_f32 v[208:209], v[94:95], v[78:79], v[208:209]
	v_pk_fma_f32 v[210:211], v[110:111], v[78:79], v[210:211]
	v_pk_fma_f32 v[212:213], v[126:127], v[78:79], v[212:213]
	v_pk_fma_f32 v[214:215], v[142:143], v[78:79], v[214:215]
	v_pk_fma_f32 v[216:217], v[158:159], v[78:79], v[216:217]
	v_pk_fma_f32 v[218:219], v[174:175], v[78:79], v[218:219]
	v_pk_fma_f32 v[220:221], v[190:191], v[78:79], v[220:221]
	v_pk_fma_f32 v[222:223], v[206:207], v[78:79], v[222:223]
	s_nop 0
	v_add_f32_e32 v14, v208, v209
	v_add_f32_e32 v15, v210, v211
	v_add_f32_e32 v12, v212, v213
	v_add_f32_e32 v13, v214, v215
	v_add_f32_e32 v10, v216, v217
	v_add_f32_e32 v11, v218, v219
	v_add_f32_e32 v8, v220, v221
	v_add_f32_e32 v9, v222, v223
	ds_write2_b32 v17, v14, v15 offset1:32
	ds_write2_b32 v17, v12, v13 offset0:64 offset1:96
	ds_write2_b32 v17, v10, v11 offset0:128 offset1:160
	ds_write2_b32 v17, v8, v9 offset0:192 offset1:224
	s_waitcnt lgkmcnt(0)
	s_barrier
	s_and_saveexec_b64 s[8:9], s[2:3]
	s_cbranch_execz .LBB0_70
	v_lshl_or_b32 v6, s12, 5, v16
	v_ashrrev_i32_e32 v7, 31, v6
	v_lshl_add_u64 v[8:9], v[6:7], 2, s[4:5]
	global_load_dword v3, v[8:9], off
	ds_read2st64_b32 v[8:9], v18 offset1:4
	ds_read2st64_b32 v[10:11], v18 offset0:8 offset1:12
	ds_read2st64_b32 v[12:13], v18 offset0:16 offset1:20
	ds_read2st64_b32 v[14:15], v18 offset0:24 offset1:28
	ds_read2st64_b32 v[20:21], v18 offset0:32 offset1:36
	ds_read2st64_b32 v[22:23], v18 offset0:40 offset1:44
	ds_read2st64_b32 v[24:25], v18 offset0:48 offset1:52
	ds_read2st64_b32 v[26:27], v18 offset0:56 offset1:60
	s_waitcnt lgkmcnt(7)
	v_add_f32_e32 v8, 0, v8
	v_add_f32_e32 v8, v8, v9
	s_waitcnt lgkmcnt(6)
	v_add_f32_e32 v8, v8, v10
	v_add_f32_e32 v8, v8, v11
	s_waitcnt lgkmcnt(5)
	v_add_f32_e32 v8, v8, v12
	v_add_f32_e32 v8, v8, v13
	s_waitcnt lgkmcnt(4)
	v_add_f32_e32 v8, v8, v14
	v_add_f32_e32 v8, v8, v15
	s_waitcnt lgkmcnt(3)
	v_add_f32_e32 v8, v8, v20
	v_add_f32_e32 v8, v8, v21
	s_waitcnt lgkmcnt(2)
	v_add_f32_e32 v8, v8, v22
	v_add_f32_e32 v8, v8, v23
	s_waitcnt lgkmcnt(1)
	v_add_f32_e32 v8, v8, v24
	v_add_f32_e32 v8, v8, v25
	v_add_u32_e32 v6, v6, v19
	s_waitcnt lgkmcnt(0)
	v_add_f32_e32 v8, v8, v26
	v_ashrrev_i32_e32 v7, 31, v6
	v_add_f32_e32 v8, v8, v27
	v_lshl_add_u64 v[6:7], v[6:7], 2, s[0:1]
	s_waitcnt vmcnt(0)
	v_add_f32_e32 v3, v8, v3
	global_store_dword v[6:7], v3, off
	s_branch .LBB0_70

	.amdhsa_kernel _Z10fwd_kernelILj1048575EEv4Args
		.amdhsa_group_segment_fixed_size 0
		.amdhsa_private_segment_fixed_size 0
		.amdhsa_kernarg_size 496
		.amdhsa_user_sgpr_count 2
		.amdhsa_user_sgpr_dispatch_ptr 0
		.amdhsa_user_sgpr_queue_ptr 0
		.amdhsa_user_sgpr_kernarg_segment_ptr 1
		.amdhsa_user_sgpr_dispatch_id 0
		.amdhsa_user_sgpr_kernarg_preload_length 0
		.amdhsa_user_sgpr_kernarg_preload_offset 0
		.amdhsa_user_sgpr_private_segment_size 0
		.amdhsa_uses_dynamic_stack 0
		.amdhsa_enable_private_segment 0
		.amdhsa_system_sgpr_workgroup_id_x 1
		.amdhsa_system_sgpr_workgroup_id_y 0
		.amdhsa_system_sgpr_workgroup_id_z 0
		.amdhsa_system_sgpr_workgroup_info 0
		.amdhsa_system_vgpr_workitem_id 2
		.amdhsa_next_free_vgpr 256
		.amdhsa_next_free_sgpr 102
		.amdhsa_accum_offset 256
		.amdhsa_reserve_vcc 1
		.amdhsa_float_round_mode_32 0
		.amdhsa_float_round_mode_16_64 0
		.amdhsa_float_denorm_mode_32 3
		.amdhsa_float_denorm_mode_16_64 3
		.amdhsa_dx10_clamp 1
		.amdhsa_ieee_mode 1
		.amdhsa_fp16_overflow 0
		.amdhsa_tg_split 0
		.amdhsa_exception_fp_ieee_invalid_op 0
		.amdhsa_exception_fp_denorm_src 0
		.amdhsa_exception_fp_ieee_div_zero 0
		.amdhsa_exception_fp_ieee_overflow 0
		.amdhsa_exception_fp_ieee_underflow 0
		.amdhsa_exception_fp_ieee_inexact 0
		.amdhsa_exception_int_div_zero 0
	.end_amdhsa_kernel

amdhsa.kernels:
  - .agpr_count:     0
    .args:
      - .offset:         0
        .size:           240
        .value_kind:     by_value
      - .offset:         240
        .size:           4
        .value_kind:     hidden_block_count_x
      - .offset:         244
        .size:           4
        .value_kind:     hidden_block_count_y
      - .offset:         248
        .size:           4
        .value_kind:     hidden_block_count_z
      - .offset:         252
        .size:           2
        .value_kind:     hidden_group_size_x
      - .offset:         254
        .size:           2
        .value_kind:     hidden_group_size_y
      - .offset:         256
        .size:           2
        .value_kind:     hidden_group_size_z
      - .offset:         258
        .size:           2
        .value_kind:     hidden_remainder_x
      - .offset:         260
        .size:           2
        .value_kind:     hidden_remainder_y
      - .offset:         262
        .size:           2
        .value_kind:     hidden_remainder_z
      - .offset:         280
        .size:           8
        .value_kind:     hidden_global_offset_x
      - .offset:         288
        .size:           8
        .value_kind:     hidden_global_offset_y
      - .offset:         296
        .size:           8
        .value_kind:     hidden_global_offset_z
      - .offset:         304
        .size:           2
        .value_kind:     hidden_grid_dims
      - .offset:         328
        .size:           8
        .value_kind:     hidden_multigrid_sync_arg
      - .offset:         360
        .size:           4
        .value_kind:     hidden_dynamic_lds_size
    .group_segment_fixed_size: 0
    .kernarg_segment_align: 8
    .kernarg_segment_size: 496
    .language:       OpenCL C
    .language_version:
      - 2
      - 0
    .max_flat_workgroup_size: 512
    .name:           _Z10fwd_kernelILj1048575EEv4Args
    .private_segment_fixed_size: 0
    .sgpr_count:     108
    .sgpr_spill_count: 126
    .symbol:         _Z10fwd_kernelILj1048575EEv4Args.kd
    .uniform_work_group_size: 1
    .uses_dynamic_stack: false
    .vgpr_count:     256
    .vgpr_spill_count: 0
    .wavefront_size: 64
